# w_in fifth round: each remaining 256x256 tile split in two row halves between workgroup c and the idle workgroup c+128 (second MMA block skipped, four row groups stored)
# baseline (speedup 1.0000x reference)
.LBB0_526:
	s_cmp_gt_i32 s87, 0
	s_mov_b64 s[8:9], -1
	s_cbranch_scc0 .LBB0_619
	s_cmp_gt_i32 s87, 1
	s_mov_b64 s[4:5], -1
	s_cbranch_scc0 .LBB0_852
	s_cmp_eq_u32 s87, 2
	s_mov_b64 s[0:1], -1
	s_cbranch_scc0 .LBB0_851
	v_mov_b32_e32 v0, v240
	s_nop 0
	v_cmp_gt_i32_e32 vcc, 12, v0
	s_and_saveexec_b64 s[0:1], vcc
	s_cbranch_execz .LBB0_533
	s_waitcnt vmcnt(0) lgkmcnt(0)
	v_mov_b64_e32 v[2:3], s[74:75]
	v_mad_i64_i32 v[2:3], s[2:3], v0, s56, v[2:3]
	s_cmpk_ge_i32 s74, 0x80
	s_cselect_b32 s98, 0x80, 0
	s_cmp_eq_u32 s56, 0x100
	s_cselect_b32 s98, s98, 0
	v_cmp_eq_u32_e32 vcc, 4, v0
	v_mov_b32_e32 v4, s98
	s_nop 1
	v_cndmask_b32_e32 v4, 0, v4, vcc
	v_sub_u32_e32 v2, v2, v4
	s_mov_b64 s[2:3], 0x480
	s_nop 0
	v_cmp_gt_i64_e32 vcc, s[2:3], v[2:3]
	v_mov_b32_e32 v3, -1
	s_and_saveexec_b64 s[4:5], vcc
	s_cbranch_execz .LBB0_532
	v_ashrrev_i32_e32 v3, 31, v2
	v_lshrrev_b32_e32 v3, 29, v3
	v_add_u32_e32 v3, v2, v3
	v_ashrrev_i32_e32 v4, 3, v3
	v_and_b32_e32 v3, -8, v3
	v_sub_u32_e32 v2, v2, v3
	v_cmp_gt_i32_e32 vcc, 0, v2
	v_mov_b32_e32 v3, 0x90
	v_mov_b32_e32 v5, 0x91
	v_cndmask_b32_e32 v3, v3, v5, vcc
	v_mul_lo_u32 v2, v2, v3
	v_add_u32_e32 v2, v2, v4
	s_mov_b32 s2, 0x38e38e39
	v_mul_hi_i32 v3, v2, s2
	v_lshrrev_b32_e32 v4, 31, v3
	v_ashrrev_i32_e32 v3, 4, v3
	v_add_u32_e32 v3, v3, v4
	v_lshlrev_b32_e32 v4, 3, v3
	v_sub_u32_e32 v5, 0x80, v4
	v_min_i32_e32 v5, 8, v5
	v_sub_u32_e32 v6, 0, v5
	v_max_i32_e32 v5, v5, v6
	v_cvt_f32_u32_e32 v6, v5
	s_movk_i32 s2, 0x48
	v_mul_lo_u32 v3, v3, s2
	v_sub_u32_e32 v2, v2, v3
	v_rcp_iflag_f32_e32 v6, v6
	v_sub_u32_e32 v7, 0, v2
	v_ashrrev_i32_e32 v3, 31, v2
	v_max_i32_e32 v2, v2, v7
	v_mul_f32_e32 v6, 0x4f7ffffe, v6
	v_cvt_u32_f32_e32 v6, v6
	v_sub_u32_e32 v7, 0, v5
	v_mul_lo_u32 v7, v7, v6
	v_mul_hi_u32 v7, v6, v7
	v_add_u32_e32 v6, v6, v7
	v_mul_hi_u32 v6, v2, v6
	v_mul_lo_u32 v6, v6, v5
	v_sub_u32_e32 v2, v2, v6
	v_sub_u32_e32 v6, v2, v5
	v_cmp_ge_u32_e32 vcc, v2, v5
	s_nop 1
	v_cndmask_b32_e32 v2, v2, v6, vcc
	v_sub_u32_e32 v6, v2, v5
	v_cmp_ge_u32_e32 vcc, v2, v5
	s_nop 1
	v_cndmask_b32_e32 v2, v2, v6, vcc
	v_xor_b32_e32 v2, v2, v3
	v_sub_u32_e32 v2, v2, v3
	v_add_u32_e32 v3, v4, v2

.LBB0_560:
	s_lshl_b64 s[2:3], s[88:89], 18
	v_readlane_b32 s4, v254, 24
	v_readlane_b32 s26, v254, 48
	s_add_u32 s10, s4, s2
	v_readlane_b32 s2, v254, 25
	v_mov_b32_e32 v141, v1
	v_readlane_b32 s27, v254, 49
	s_addc_u32 s11, s2, s3
	s_and_b32 s22, s1, 3
	s_add_i32 m0, s39, 0x18000
	v_lshl_add_u64 v[2:3], v[2:3], 0, s[92:93]
	v_lshl_add_u64 v[18:19], s[26:27], 0, v[140:141]
	v_mov_b32_e32 v139, v1
	s_lshl_b32 s1, s13, 13
	s_lshl_b32 s4, s22, 12
	s_waitcnt vmcnt(2)
	s_barrier
	global_load_lds_dwordx4 v[2:3], off
	v_lshl_add_u64 v[2:3], v[4:5], 0, s[92:93]
	s_add_i32 m0, s39, 0x1a000
	s_add_i32 s43, s39, 0x8000
	s_add_i32 s44, s39, 0xa000
	v_lshl_add_u64 v[20:21], s[26:27], 0, v[138:139]
	global_load_lds_dwordx4 v[2:3], off
	v_lshl_add_u64 v[2:3], v[18:19], 0, s[92:93]
	s_mov_b32 m0, s43
	s_add_u32 s2, s30, 0x40080
	global_load_lds_dwordx4 v[2:3], off
	v_lshl_add_u64 v[2:3], v[20:21], 0, s[92:93]
	s_mov_b32 m0, s44
	s_addc_u32 s3, s31, 0
	global_load_lds_dwordx4 v[2:3], off
	s_add_i32 m0, s39, 0x1c000
	v_lshl_add_u64 v[2:3], s[2:3], 0, v[0:1]
	global_load_lds_dwordx4 v[2:3], off
	v_lshl_add_u64 v[2:3], s[2:3], 0, v[14:15]
	s_add_i32 m0, s39, 0x1e000
	v_bfe_u32 v4, v8, 4, 2
	global_load_lds_dwordx4 v[2:3], off
	v_xor_b32_e32 v2, 16, v241
	v_cmp_lt_i32_e32 vcc, v2, v242
	v_and_b32_e32 v3, 15, v8
	v_lshl_or_b32 v197, s13, 6, v3
	v_cndmask_b32_e32 v2, v241, v2, vcc
	v_lshlrev_b32_e32 v192, 2, v2
	v_xor_b32_e32 v2, 32, v241
	v_cmp_lt_i32_e32 vcc, v2, v242
	v_lshlrev_b32_e32 v198, 2, v197
	v_and_b32_e32 v18, 32, v198
	v_cndmask_b32_e32 v2, v241, v2, vcc
	v_lshlrev_b32_e32 v193, 2, v2
	v_xor_b32_e32 v2, 2, v241
	v_cmp_lt_i32_e32 vcc, v2, v242
	s_cmpk_lt_u32 s0, 0x100
	s_cselect_b64 s[18:19], -1, 0
	v_cndmask_b32_e32 v2, v241, v2, vcc
	v_lshlrev_b32_e32 v194, 2, v2
	v_xor_b32_e32 v2, 4, v241
	v_cmp_lt_i32_e32 vcc, v2, v242
	s_bitcmp0_b32 s0, 6
	v_cmp_eq_u32_e64 s[8:9], 0, v3
	v_cndmask_b32_e32 v2, v241, v2, vcc
	v_lshlrev_b32_e32 v195, 2, v2
	v_xor_b32_e32 v2, 8, v241
	v_cmp_lt_i32_e32 vcc, v2, v242
	s_cselect_b64 s[20:21], -1, 0
	v_lshlrev_b32_e32 v8, 2, v8
	v_cndmask_b32_e32 v2, v241, v2, vcc
	v_lshlrev_b32_e32 v196, 2, v2
	v_lshlrev_b32_e32 v2, 4, v4
	v_lshl_or_b32 v13, v3, 6, v2
	v_bitop3_b32 v18, v13, s1, v18 bitop3:0xde
	v_readlane_b32 s0, v254, 12
	v_mov_b32_e32 v3, v1
	v_readlane_b32 s1, v254, 13
	s_waitcnt vmcnt(6)
	v_lshlrev_b32_e32 v5, 3, v4
	v_and_b32_e32 v8, 32, v8
	v_lshl_add_u64 v[142:143], s[0:1], 0, v[2:3]
	s_lshl_b32 s0, s22, 7
	s_add_u32 s0, s10, s0
	s_addc_u32 s1, s11, 0
	v_lshlrev_b32_e32 v2, 5, v4
	v_lshl_add_u64 v[144:145], s[0:1], 0, v[2:3]
	v_lshlrev_b32_e32 v2, 14, v11
	v_and_b32_e32 v2, 0xffff8000, v2
	v_lshl_add_u32 v2, v10, 11, v2
	v_and_b32_e32 v3, 1, v11
	v_lshl_or_b32 v2, v3, 6, v2
	v_lshl_add_u32 v146, v12, 1, v2
	v_lshlrev_b32_e32 v2, 14, v6
	v_and_b32_e32 v2, 0xffff8000, v2
	v_lshl_add_u32 v2, v7, 11, v2
	v_and_b32_e32 v3, 1, v6
	v_readlane_b32 s0, v254, 44
	v_lshl_or_b32 v2, v3, 6, v2
	v_readlane_b32 s1, v254, 45
	v_bitop3_b32 v199, v13, s4, v8 bitop3:0xde
	s_mov_b32 s2, 0
	v_cmp_eq_u32_e64 s[4:5], 0, v4
	v_cmp_gt_u32_e64 s[6:7], 2, v4
	v_lshl_or_b32 v200, s22, 5, v5
	v_mov_b32_e32 v147, v1
	v_lshl_add_u32 v148, v9, 1, v2
	v_mov_b32_e32 v149, v1
	v_add_u32_e32 v201, 0, v18
	v_readlane_b32 s47, v254, 41
	s_mov_b32 s46, s0
	s_mov_b32 s99, 0
	s_mov_b64 s[0:1], s[26:27]
	s_barrier
	s_branch .LBB0_563

.LBB0_562:
	s_andn2_b64 vcc, exec, s[0:1]
	s_mov_b32 s47, s22
	s_mov_b32 s46, s24
	s_mov_b32 s99, s98
	s_mov_b64 s[30:31], s[28:29]
	s_mov_b64 s[0:1], s[26:27]
	s_mov_b32 s2, s45
	s_cbranch_vccz .LBB0_849
.LBB0_563:
	s_add_i32 s45, s2, 1
	s_mul_i32 s3, s45, s70
	s_mul_hi_u32 s10, s45, s56
	s_add_i32 s10, s10, s3
	s_mul_i32 s3, s45, s56
	s_add_u32 s26, s3, s74
	s_addc_u32 s27, s10, s75
	s_mov_b32 s98, 0
	s_cmp_lg_u32 s45, 4
	s_cbranch_scc1 .Lht_hdr_done
	s_cmp_lg_u32 s56, 0x100
	s_cbranch_scc1 .Lht_hdr_done
	s_mov_b32 s98, 1
	s_cmpk_lt_i32 s74, 0x80
	s_cbranch_scc1 .Lht_hdr_done
	s_mov_b32 s98, 2
	s_sub_u32 s26, s26, 0x80
	s_subb_u32 s27, s27, 0
.Lht_hdr_done:
	v_mov_b64_e32 v[2:3], 0x480
	v_cmp_lt_i64_e64 s[10:11], s[26:27], v[2:3]
	v_mov_b64_e32 v[2:3], 0x47f
	v_cmp_gt_i64_e32 vcc, s[26:27], v[2:3]
	s_cbranch_vccnz .LBB0_565
	s_ashr_i32 s3, s26, 31
	s_lshr_b32 s3, s3, 29
	s_add_i32 s3, s26, s3
	s_ashr_i32 s22, s3, 3
	s_and_b32 s3, s3, -8
	s_sub_i32 s3, s26, s3
	s_cmp_lt_i32 s3, 0
	s_movk_i32 s23, 0x91
	s_cselect_b32 s23, s23, 0x90
	s_mul_i32 s3, s3, s23
	s_add_i32 s3, s3, s22
	s_mul_hi_i32 s22, s3, 0x38e38e39
	s_lshr_b32 s23, s22, 31
	s_ashr_i32 s22, s22, 4
	s_add_i32 s22, s22, s23
	s_lshl_b32 s23, s22, 3
	s_sub_i32 s24, 0x80, s23
	s_min_i32 s24, s24, 8
	s_abs_i32 s25, s24
	v_cvt_f32_u32_e32 v2, s25
	s_sub_i32 s27, 0, s25
	s_mulk_i32 s22, 0x48
	s_sub_i32 s3, s3, s22
	v_rcp_iflag_f32_e32 v2, v2
	s_abs_i32 s22, s3
	s_xor_b32 s26, s3, s24
	s_ashr_i32 s26, s26, 31
	v_mul_f32_e32 v2, 0x4f7ffffe, v2
	v_cvt_u32_f32_e32 v2, v2
	s_nop 0
	v_readfirstlane_b32 s28, v2
	s_mul_i32 s27, s27, s28
	s_mul_hi_u32 s27, s28, s27
	s_add_i32 s28, s28, s27
	s_mul_hi_u32 s27, s22, s28
	s_mul_i32 s28, s27, s25
	s_sub_i32 s22, s22, s28
	s_add_i32 s29, s27, 1
	s_sub_i32 s28, s22, s25
	s_cmp_ge_u32 s22, s25
	s_cselect_b32 s27, s29, s27
	s_cselect_b32 s22, s28, s22
	s_add_i32 s28, s27, 1
	s_cmp_ge_u32 s22, s25
	s_cselect_b32 s22, s28, s27
	s_xor_b32 s22, s22, s26
	s_sub_i32 s22, s22, s26
	s_mul_i32 s24, s22, s24
	s_sub_i32 s3, s3, s24
	s_add_i32 s24, s23, s3
.LBB0_565:
	s_ashr_i32 s25, s24, 31
	s_lshl_b64 s[26:27], s[24:25], 19
	s_add_u32 s26, s84, s26
	s_addc_u32 s27, s85, s27
	s_cmp_eq_u32 s98, 2
	s_cselect_b32 s28, 0x40000, 0
	s_add_u32 s26, s26, s28
	s_addc_u32 s27, s27, 0
	s_and_b64 s[28:29], s[10:11], exec
	s_cselect_b32 s3, s27, s1
	s_cselect_b32 s25, s26, s0
	s_ashr_i32 s23, s22, 31
	s_lshl_b64 s[28:29], s[22:23], 19
	s_add_u32 s28, s37, s28
	s_addc_u32 s29, s38, s29
	s_and_b64 s[34:35], s[10:11], exec
	s_cselect_b32 s23, s29, s31
	s_cselect_b32 s48, s28, s30
	s_add_u32 s0, s0, 0x40080
	s_addc_u32 s1, s1, 0
	s_add_u32 s49, s30, 0x100
	v_mov_b32_e32 v2, 0
	s_addc_u32 s50, s31, 0
	s_mov_b32 s51, -2
	v_mov_b32_e32 v3, v2
	s_waitcnt lgkmcnt(0)
	v_mov_b32_e32 v4, v2
	v_mov_b32_e32 v5, v2
	v_mov_b32_e32 v6, v2
	v_mov_b32_e32 v7, v2
	v_mov_b32_e32 v8, v2
	v_mov_b32_e32 v9, v2
	v_mov_b32_e32 v22, v2
	v_mov_b32_e32 v23, v2
	v_mov_b32_e32 v24, v2
	v_mov_b32_e32 v25, v2
	v_mov_b32_e32 v26, v2
	v_mov_b32_e32 v27, v2
	v_mov_b32_e32 v28, v2
	v_mov_b32_e32 v29, v2
	v_mov_b32_e32 v38, v2
	v_mov_b32_e32 v39, v2
	v_mov_b32_e32 v40, v2
	v_mov_b32_e32 v41, v2
	v_mov_b32_e32 v42, v2
	v_mov_b32_e32 v43, v2
	v_mov_b32_e32 v44, v2
	v_mov_b32_e32 v45, v2
	v_mov_b32_e32 v54, v2
	v_mov_b32_e32 v55, v2
	v_mov_b32_e32 v56, v2
	v_mov_b32_e32 v57, v2
	v_mov_b32_e32 v58, v2
	v_mov_b32_e32 v59, v2
	v_mov_b32_e32 v60, v2
	v_mov_b32_e32 v61, v2
	v_mov_b32_e32 v10, v2
	v_mov_b32_e32 v11, v2
	v_mov_b32_e32 v12, v2
	v_mov_b32_e32 v13, v2
	v_mov_b32_e32 v18, v2
	v_mov_b32_e32 v19, v2
	v_mov_b32_e32 v20, v2
	v_mov_b32_e32 v21, v2
	v_mov_b32_e32 v30, v2
	v_mov_b32_e32 v31, v2
	v_mov_b32_e32 v32, v2
	v_mov_b32_e32 v33, v2
	v_mov_b32_e32 v34, v2
	v_mov_b32_e32 v35, v2
	v_mov_b32_e32 v36, v2
	v_mov_b32_e32 v37, v2
	v_mov_b32_e32 v46, v2
	v_mov_b32_e32 v47, v2
	v_mov_b32_e32 v48, v2
	v_mov_b32_e32 v49, v2
	v_mov_b32_e32 v50, v2
	v_mov_b32_e32 v51, v2
	v_mov_b32_e32 v52, v2
	v_mov_b32_e32 v53, v2
	v_mov_b32_e32 v62, v2
	v_mov_b32_e32 v63, v2
	v_mov_b32_e32 v64, v2
	v_mov_b32_e32 v65, v2
	v_mov_b32_e32 v66, v2
	v_mov_b32_e32 v67, v2
	v_mov_b32_e32 v68, v2
	v_mov_b32_e32 v69, v2
	v_mov_b32_e32 v70, v2
	v_mov_b32_e32 v71, v2
	v_mov_b32_e32 v72, v2
	v_mov_b32_e32 v73, v2
	v_mov_b32_e32 v74, v2
	v_mov_b32_e32 v75, v2
	v_mov_b32_e32 v76, v2
	v_mov_b32_e32 v77, v2
	v_mov_b32_e32 v86, v2
	v_mov_b32_e32 v87, v2
	v_mov_b32_e32 v88, v2
	v_mov_b32_e32 v89, v2
	v_mov_b32_e32 v90, v2
	v_mov_b32_e32 v91, v2
	v_mov_b32_e32 v92, v2
	v_mov_b32_e32 v93, v2
	v_mov_b32_e32 v102, v2
	v_mov_b32_e32 v103, v2
	v_mov_b32_e32 v104, v2
	v_mov_b32_e32 v105, v2
	v_mov_b32_e32 v106, v2
	v_mov_b32_e32 v107, v2
	v_mov_b32_e32 v108, v2
	v_mov_b32_e32 v109, v2
	v_mov_b32_e32 v118, v2
	v_mov_b32_e32 v119, v2
	v_mov_b32_e32 v120, v2
	v_mov_b32_e32 v121, v2
	v_mov_b32_e32 v122, v2
	v_mov_b32_e32 v123, v2
	v_mov_b32_e32 v124, v2
	v_mov_b32_e32 v125, v2
	v_mov_b32_e32 v78, v2
	v_mov_b32_e32 v79, v2
	v_mov_b32_e32 v80, v2
	v_mov_b32_e32 v81, v2
	v_mov_b32_e32 v82, v2
	v_mov_b32_e32 v83, v2
	v_mov_b32_e32 v84, v2
	v_mov_b32_e32 v85, v2
	v_mov_b32_e32 v94, v2
	v_mov_b32_e32 v95, v2
	v_mov_b32_e32 v96, v2
	v_mov_b32_e32 v97, v2
	v_mov_b32_e32 v98, v2
	v_mov_b32_e32 v99, v2
	v_mov_b32_e32 v100, v2
	v_mov_b32_e32 v101, v2
	v_mov_b32_e32 v110, v2
	v_mov_b32_e32 v111, v2
	v_mov_b32_e32 v112, v2
	v_mov_b32_e32 v113, v2
	v_mov_b32_e32 v114, v2
	v_mov_b32_e32 v115, v2
	v_mov_b32_e32 v116, v2
	v_mov_b32_e32 v117, v2
	v_mov_b32_e32 v126, v2
	v_mov_b32_e32 v127, v2
	v_mov_b32_e32 v128, v2
	v_mov_b32_e32 v129, v2
	v_mov_b32_e32 v130, v2
	v_mov_b32_e32 v131, v2
	v_mov_b32_e32 v132, v2
	v_mov_b32_e32 v133, v2
.LBB0_566:
	s_add_u32 s30, s0, 0xfffc0080
	s_addc_u32 s31, s1, -1
	s_add_i32 s52, 0, 0x10000
	s_cmp_eq_u32 s51, 12
	s_cselect_b32 s35, s3, s31
	s_cselect_b32 s34, s25, s30
	s_cselect_b32 s31, s23, s50
	s_cselect_b32 s30, s48, s49
	s_add_i32 s54, 0, 0x14000
	v_add_u32_e32 v158, s52, v199
	v_add_u32_e32 v174, s54, v199
	ds_read_b128 v[134:137], v158
	ds_read_b128 v[150:153], v158 offset:1024
	ds_read_b128 v[154:157], v158 offset:2048
	ds_read_b128 v[158:161], v158 offset:3072
	ds_read_b128 v[162:165], v174
	ds_read_b128 v[166:169], v174 offset:1024
	ds_read_b128 v[170:173], v174 offset:2048
	ds_read_b128 v[182:185], v174 offset:3072
	v_lshl_add_u64 v[174:175], s[0:1], 0, v[146:147]
	s_add_i32 m0, s39, 0xc000
	ds_read_b128 v[186:189], v201
	ds_read_b128 v[202:205], v201 offset:1024
	ds_read_b128 v[206:209], v201 offset:2048
	ds_read_b128 v[210:213], v201 offset:3072
	ds_read_b128 v[214:217], v201 offset:4096
	ds_read_b128 v[218:221], v201 offset:5120
	ds_read_b128 v[222:225], v201 offset:6144
	ds_read_b128 v[226:229], v201 offset:7168
	global_load_lds_dwordx4 v[174:175], off
	v_lshl_add_u64 v[174:175], s[0:1], 0, v[148:149]
	s_add_i32 m0, s39, 0xe000
	s_nop 0
	global_load_lds_dwordx4 v[174:175], off
	s_waitcnt vmcnt(8)
	s_waitcnt lgkmcnt(0)
	s_barrier
	s_setprio 1
	s_waitcnt lgkmcnt(0)
	v_mfma_f32_16x16x32_bf16 v[130:133], v[134:137], v[186:189], v[130:133]
	v_mfma_f32_16x16x32_bf16 v[130:133], v[150:153], v[202:205], v[130:133]
	v_mfma_f32_16x16x32_bf16 v[126:129], v[154:157], v[186:189], v[126:129]
	v_mfma_f32_16x16x32_bf16 v[126:129], v[158:161], v[202:205], v[126:129]
	v_mfma_f32_16x16x32_bf16 v[114:117], v[134:137], v[206:209], v[114:117]
	v_mfma_f32_16x16x32_bf16 v[114:117], v[150:153], v[210:213], v[114:117]
	v_mfma_f32_16x16x32_bf16 v[110:113], v[154:157], v[206:209], v[110:113]
	v_mfma_f32_16x16x32_bf16 v[110:113], v[158:161], v[210:213], v[110:113]
	v_mfma_f32_16x16x32_bf16 v[98:101], v[134:137], v[214:217], v[98:101]
	v_mfma_f32_16x16x32_bf16 v[98:101], v[150:153], v[218:221], v[98:101]
	v_mfma_f32_16x16x32_bf16 v[94:97], v[154:157], v[214:217], v[94:97]
	v_mfma_f32_16x16x32_bf16 v[94:97], v[158:161], v[218:221], v[94:97]
	v_mfma_f32_16x16x32_bf16 v[82:85], v[134:137], v[222:225], v[82:85]
	v_mfma_f32_16x16x32_bf16 v[82:85], v[150:153], v[226:229], v[82:85]
	v_mfma_f32_16x16x32_bf16 v[78:81], v[154:157], v[222:225], v[78:81]
	v_mfma_f32_16x16x32_bf16 v[78:81], v[158:161], v[226:229], v[78:81]
	s_setprio 0
	s_setprio 1
	v_mfma_f32_16x16x32_bf16 v[122:125], v[162:165], v[186:189], v[122:125]
	v_mfma_f32_16x16x32_bf16 v[122:125], v[166:169], v[202:205], v[122:125]
	v_mfma_f32_16x16x32_bf16 v[118:121], v[170:173], v[186:189], v[118:121]
	v_mfma_f32_16x16x32_bf16 v[118:121], v[182:185], v[202:205], v[118:121]
	v_mfma_f32_16x16x32_bf16 v[106:109], v[162:165], v[206:209], v[106:109]
	v_mfma_f32_16x16x32_bf16 v[106:109], v[166:169], v[210:213], v[106:109]
	v_mfma_f32_16x16x32_bf16 v[102:105], v[170:173], v[206:209], v[102:105]
	v_mfma_f32_16x16x32_bf16 v[102:105], v[182:185], v[210:213], v[102:105]
	v_mfma_f32_16x16x32_bf16 v[90:93], v[162:165], v[214:217], v[90:93]
	v_mfma_f32_16x16x32_bf16 v[90:93], v[166:169], v[218:221], v[90:93]
	v_mfma_f32_16x16x32_bf16 v[86:89], v[170:173], v[214:217], v[86:89]
	v_mfma_f32_16x16x32_bf16 v[86:89], v[182:185], v[218:221], v[86:89]
	v_mfma_f32_16x16x32_bf16 v[74:77], v[162:165], v[222:225], v[74:77]
	v_mfma_f32_16x16x32_bf16 v[74:77], v[166:169], v[226:229], v[74:77]
	v_mfma_f32_16x16x32_bf16 v[70:73], v[170:173], v[222:225], v[70:73]
	v_mfma_f32_16x16x32_bf16 v[70:73], v[182:185], v[226:229], v[70:73]
	s_setprio 0
	s_barrier
	s_add_i32 s52, s52, s36
	v_lshl_add_u64 v[174:175], s[30:31], 0, v[0:1]
	s_mov_b32 m0, s52
	ds_read_b128 v[186:189], v201 offset:16384
	ds_read_b128 v[202:205], v201 offset:17408
	ds_read_b128 v[206:209], v201 offset:18432
	ds_read_b128 v[210:213], v201 offset:19456
	ds_read_b128 v[214:217], v201 offset:20480
	ds_read_b128 v[218:221], v201 offset:21504
	ds_read_b128 v[222:225], v201 offset:22528
	ds_read_b128 v[226:229], v201 offset:23552
	global_load_lds_dwordx4 v[174:175], off
	s_add_i32 m0, s52, 0x2000
	s_add_u32 s52, s30, 0x40000
	v_lshl_add_u64 v[190:191], s[30:31], 0, v[14:15]
	s_addc_u32 s53, s31, 0
	s_add_i32 s54, s54, s36
	global_load_lds_dwordx4 v[190:191], off
	v_lshl_add_u64 v[230:231], s[52:53], 0, v[0:1]
	s_mov_b32 m0, s54
	v_lshl_add_u64 v[232:233], s[34:35], 0, v[138:139]
	global_load_lds_dwordx4 v[230:231], off
	v_lshl_add_u64 v[230:231], s[52:53], 0, v[14:15]
	s_add_i32 m0, s54, 0x2000
	s_nop 0
	global_load_lds_dwordx4 v[230:231], off
	v_lshl_add_u64 v[230:231], s[34:35], 0, v[140:141]
	s_mov_b32 m0, s39
	s_nop 0
	global_load_lds_dwordx4 v[230:231], off
	s_mov_b32 m0, s40
	s_nop 0
	global_load_lds_dwordx4 v[232:233], off
	s_waitcnt vmcnt(8)
	s_waitcnt lgkmcnt(0)
	s_barrier
	s_cmp_lg_u32 s99, 0
	s_cbranch_scc1 .Lht_skip_a
	s_setprio 1
	s_waitcnt lgkmcnt(0)
	v_mfma_f32_16x16x32_bf16 v[66:69], v[134:137], v[186:189], v[66:69]
	v_mfma_f32_16x16x32_bf16 v[66:69], v[150:153], v[202:205], v[66:69]
	v_mfma_f32_16x16x32_bf16 v[62:65], v[154:157], v[186:189], v[62:65]
	v_mfma_f32_16x16x32_bf16 v[62:65], v[158:161], v[202:205], v[62:65]
	v_mfma_f32_16x16x32_bf16 v[50:53], v[134:137], v[206:209], v[50:53]
	v_mfma_f32_16x16x32_bf16 v[50:53], v[150:153], v[210:213], v[50:53]
	v_mfma_f32_16x16x32_bf16 v[46:49], v[154:157], v[206:209], v[46:49]
	v_mfma_f32_16x16x32_bf16 v[46:49], v[158:161], v[210:213], v[46:49]
	v_mfma_f32_16x16x32_bf16 v[34:37], v[134:137], v[214:217], v[34:37]
	v_mfma_f32_16x16x32_bf16 v[34:37], v[150:153], v[218:221], v[34:37]
	v_mfma_f32_16x16x32_bf16 v[30:33], v[154:157], v[214:217], v[30:33]
	v_mfma_f32_16x16x32_bf16 v[30:33], v[158:161], v[218:221], v[30:33]
	v_mfma_f32_16x16x32_bf16 v[18:21], v[134:137], v[222:225], v[18:21]
	v_mfma_f32_16x16x32_bf16 v[18:21], v[150:153], v[226:229], v[18:21]
	v_mfma_f32_16x16x32_bf16 v[10:13], v[154:157], v[222:225], v[10:13]
	v_mfma_f32_16x16x32_bf16 v[10:13], v[158:161], v[226:229], v[10:13]
	s_setprio 0
	s_setprio 1
	v_mfma_f32_16x16x32_bf16 v[58:61], v[162:165], v[186:189], v[58:61]
	v_mfma_f32_16x16x32_bf16 v[58:61], v[166:169], v[202:205], v[58:61]
	v_mfma_f32_16x16x32_bf16 v[54:57], v[170:173], v[186:189], v[54:57]
	v_mfma_f32_16x16x32_bf16 v[54:57], v[182:185], v[202:205], v[54:57]
	v_mfma_f32_16x16x32_bf16 v[42:45], v[162:165], v[206:209], v[42:45]
	v_mfma_f32_16x16x32_bf16 v[42:45], v[166:169], v[210:213], v[42:45]
	v_mfma_f32_16x16x32_bf16 v[38:41], v[170:173], v[206:209], v[38:41]
	v_mfma_f32_16x16x32_bf16 v[38:41], v[182:185], v[210:213], v[38:41]
	v_mfma_f32_16x16x32_bf16 v[26:29], v[162:165], v[214:217], v[26:29]
	v_mfma_f32_16x16x32_bf16 v[26:29], v[166:169], v[218:221], v[26:29]
	v_mfma_f32_16x16x32_bf16 v[22:25], v[170:173], v[214:217], v[22:25]
	v_mfma_f32_16x16x32_bf16 v[22:25], v[182:185], v[218:221], v[22:25]
	v_mfma_f32_16x16x32_bf16 v[6:9], v[162:165], v[222:225], v[6:9]
	v_mfma_f32_16x16x32_bf16 v[6:9], v[166:169], v[226:229], v[6:9]
	v_mfma_f32_16x16x32_bf16 v[2:5], v[170:173], v[222:225], v[2:5]
	v_mfma_f32_16x16x32_bf16 v[2:5], v[182:185], v[226:229], v[2:5]
	s_setprio 0
.Lht_skip_a:
	s_barrier
	s_add_i32 s52, 0, 0x18000
	s_add_i32 s53, 0, 0x1c000
	v_add_u32_e32 v158, s52, v199
	v_add_u32_e32 v182, s53, v199
	ds_read_b128 v[134:137], v158
	ds_read_b128 v[150:153], v158 offset:1024
	ds_read_b128 v[154:157], v158 offset:2048
	ds_read_b128 v[158:161], v158 offset:3072
	ds_read_b128 v[162:165], v182
	ds_read_b128 v[166:169], v182 offset:1024
	ds_read_b128 v[170:173], v182 offset:2048
	ds_read_b128 v[182:185], v182 offset:3072
	s_add_u32 s34, s34, 0x40000
	s_addc_u32 s35, s35, 0
	s_mov_b32 m0, s41
	v_lshl_add_u64 v[234:235], s[34:35], 0, v[140:141]
	ds_read_b128 v[186:189], v201 offset:32768
	ds_read_b128 v[202:205], v201 offset:33792
	ds_read_b128 v[206:209], v201 offset:34816
	ds_read_b128 v[210:213], v201 offset:35840
	ds_read_b128 v[214:217], v201 offset:36864
	ds_read_b128 v[218:221], v201 offset:37888
	ds_read_b128 v[222:225], v201 offset:38912
	ds_read_b128 v[226:229], v201 offset:39936
	global_load_lds_dwordx4 v[234:235], off
	v_lshl_add_u64 v[234:235], s[34:35], 0, v[138:139]
	s_mov_b32 m0, s42
	s_nop 0
	global_load_lds_dwordx4 v[234:235], off
	s_waitcnt vmcnt(8)
	s_waitcnt lgkmcnt(0)
	s_barrier
	s_setprio 1
	s_waitcnt lgkmcnt(0)
	v_mfma_f32_16x16x32_bf16 v[130:133], v[134:137], v[186:189], v[130:133]
	v_mfma_f32_16x16x32_bf16 v[130:133], v[150:153], v[202:205], v[130:133]
	v_mfma_f32_16x16x32_bf16 v[126:129], v[154:157], v[186:189], v[126:129]
	v_mfma_f32_16x16x32_bf16 v[126:129], v[158:161], v[202:205], v[126:129]
	v_mfma_f32_16x16x32_bf16 v[114:117], v[134:137], v[206:209], v[114:117]
	v_mfma_f32_16x16x32_bf16 v[114:117], v[150:153], v[210:213], v[114:117]
	v_mfma_f32_16x16x32_bf16 v[110:113], v[154:157], v[206:209], v[110:113]
	v_mfma_f32_16x16x32_bf16 v[110:113], v[158:161], v[210:213], v[110:113]
	v_mfma_f32_16x16x32_bf16 v[98:101], v[134:137], v[214:217], v[98:101]
	v_mfma_f32_16x16x32_bf16 v[98:101], v[150:153], v[218:221], v[98:101]
	v_mfma_f32_16x16x32_bf16 v[94:97], v[154:157], v[214:217], v[94:97]
	v_mfma_f32_16x16x32_bf16 v[94:97], v[158:161], v[218:221], v[94:97]
	v_mfma_f32_16x16x32_bf16 v[82:85], v[134:137], v[222:225], v[82:85]
	v_mfma_f32_16x16x32_bf16 v[82:85], v[150:153], v[226:229], v[82:85]
	v_mfma_f32_16x16x32_bf16 v[78:81], v[154:157], v[222:225], v[78:81]
	v_mfma_f32_16x16x32_bf16 v[78:81], v[158:161], v[226:229], v[78:81]
	s_setprio 0
	s_setprio 1
	v_mfma_f32_16x16x32_bf16 v[122:125], v[162:165], v[186:189], v[122:125]
	v_mfma_f32_16x16x32_bf16 v[122:125], v[166:169], v[202:205], v[122:125]
	v_mfma_f32_16x16x32_bf16 v[118:121], v[170:173], v[186:189], v[118:121]
	v_mfma_f32_16x16x32_bf16 v[118:121], v[182:185], v[202:205], v[118:121]
	v_mfma_f32_16x16x32_bf16 v[106:109], v[162:165], v[206:209], v[106:109]
	v_mfma_f32_16x16x32_bf16 v[106:109], v[166:169], v[210:213], v[106:109]
	v_mfma_f32_16x16x32_bf16 v[102:105], v[170:173], v[206:209], v[102:105]
	v_mfma_f32_16x16x32_bf16 v[102:105], v[182:185], v[210:213], v[102:105]
	v_mfma_f32_16x16x32_bf16 v[90:93], v[162:165], v[214:217], v[90:93]
	v_mfma_f32_16x16x32_bf16 v[90:93], v[166:169], v[218:221], v[90:93]
	v_mfma_f32_16x16x32_bf16 v[86:89], v[170:173], v[214:217], v[86:89]
	v_mfma_f32_16x16x32_bf16 v[86:89], v[182:185], v[218:221], v[86:89]
	v_mfma_f32_16x16x32_bf16 v[74:77], v[162:165], v[222:225], v[74:77]
	v_mfma_f32_16x16x32_bf16 v[74:77], v[166:169], v[226:229], v[74:77]
	v_mfma_f32_16x16x32_bf16 v[70:73], v[170:173], v[222:225], v[70:73]
	v_mfma_f32_16x16x32_bf16 v[70:73], v[182:185], v[226:229], v[70:73]
	s_setprio 0
	s_barrier
	s_add_i32 s34, s52, s36
	v_lshl_add_u64 v[174:175], v[174:175], 0, s[92:93]
	s_mov_b32 m0, s34
	ds_read_b128 v[186:189], v201 offset:49152
	ds_read_b128 v[202:205], v201 offset:50176
	ds_read_b128 v[206:209], v201 offset:51200
	ds_read_b128 v[210:213], v201 offset:52224
	ds_read_b128 v[214:217], v201 offset:53248
	ds_read_b128 v[218:221], v201 offset:54272
	ds_read_b128 v[222:225], v201 offset:55296
	ds_read_b128 v[226:229], v201 offset:56320
	global_load_lds_dwordx4 v[174:175], off
	s_add_i32 m0, s34, 0x2000
	s_add_u32 s30, s30, 0x40080
	v_lshl_add_u64 v[174:175], v[190:191], 0, s[92:93]
	s_addc_u32 s31, s31, 0
	s_add_i32 s34, s53, s36
	global_load_lds_dwordx4 v[174:175], off
	v_lshl_add_u64 v[174:175], s[30:31], 0, v[0:1]
	s_mov_b32 m0, s34
	s_nop 0
	global_load_lds_dwordx4 v[174:175], off
	v_lshl_add_u64 v[174:175], s[30:31], 0, v[14:15]
	s_add_i32 m0, s34, 0x2000
	s_nop 0
	global_load_lds_dwordx4 v[174:175], off
	v_lshl_add_u64 v[174:175], v[230:231], 0, s[92:93]
	s_mov_b32 m0, s43
	s_nop 0
	global_load_lds_dwordx4 v[174:175], off
	v_lshl_add_u64 v[174:175], v[232:233], 0, s[92:93]
	s_mov_b32 m0, s44
	s_nop 0
	global_load_lds_dwordx4 v[174:175], off
	s_waitcnt vmcnt(8)
	s_waitcnt lgkmcnt(0)
	s_barrier
	s_cmp_lg_u32 s99, 0
	s_cbranch_scc1 .Lht_skip_b
	s_setprio 1
	s_waitcnt lgkmcnt(0)
	v_mfma_f32_16x16x32_bf16 v[66:69], v[134:137], v[186:189], v[66:69]
	v_mfma_f32_16x16x32_bf16 v[66:69], v[150:153], v[202:205], v[66:69]
	v_mfma_f32_16x16x32_bf16 v[62:65], v[154:157], v[186:189], v[62:65]
	v_mfma_f32_16x16x32_bf16 v[62:65], v[158:161], v[202:205], v[62:65]
	v_mfma_f32_16x16x32_bf16 v[50:53], v[134:137], v[206:209], v[50:53]
	v_mfma_f32_16x16x32_bf16 v[50:53], v[150:153], v[210:213], v[50:53]
	v_mfma_f32_16x16x32_bf16 v[46:49], v[154:157], v[206:209], v[46:49]
	v_mfma_f32_16x16x32_bf16 v[46:49], v[158:161], v[210:213], v[46:49]
	v_mfma_f32_16x16x32_bf16 v[34:37], v[134:137], v[214:217], v[34:37]
	v_mfma_f32_16x16x32_bf16 v[34:37], v[150:153], v[218:221], v[34:37]
	v_mfma_f32_16x16x32_bf16 v[30:33], v[154:157], v[214:217], v[30:33]
	v_mfma_f32_16x16x32_bf16 v[30:33], v[158:161], v[218:221], v[30:33]
	v_mfma_f32_16x16x32_bf16 v[18:21], v[134:137], v[222:225], v[18:21]
	v_mfma_f32_16x16x32_bf16 v[18:21], v[150:153], v[226:229], v[18:21]
	v_mfma_f32_16x16x32_bf16 v[10:13], v[154:157], v[222:225], v[10:13]
	v_mfma_f32_16x16x32_bf16 v[10:13], v[158:161], v[226:229], v[10:13]
	s_setprio 0
	s_setprio 1
	v_mfma_f32_16x16x32_bf16 v[58:61], v[162:165], v[186:189], v[58:61]
	v_mfma_f32_16x16x32_bf16 v[58:61], v[166:169], v[202:205], v[58:61]
	v_mfma_f32_16x16x32_bf16 v[54:57], v[170:173], v[186:189], v[54:57]
	v_mfma_f32_16x16x32_bf16 v[54:57], v[182:185], v[202:205], v[54:57]
	v_mfma_f32_16x16x32_bf16 v[42:45], v[162:165], v[206:209], v[42:45]
	v_mfma_f32_16x16x32_bf16 v[42:45], v[166:169], v[210:213], v[42:45]
	v_mfma_f32_16x16x32_bf16 v[38:41], v[170:173], v[206:209], v[38:41]
	v_mfma_f32_16x16x32_bf16 v[38:41], v[182:185], v[210:213], v[38:41]
	v_mfma_f32_16x16x32_bf16 v[26:29], v[162:165], v[214:217], v[26:29]
	v_mfma_f32_16x16x32_bf16 v[26:29], v[166:169], v[218:221], v[26:29]
	v_mfma_f32_16x16x32_bf16 v[22:25], v[170:173], v[214:217], v[22:25]
	v_mfma_f32_16x16x32_bf16 v[22:25], v[182:185], v[218:221], v[22:25]
	v_mfma_f32_16x16x32_bf16 v[6:9], v[162:165], v[222:225], v[6:9]
	v_mfma_f32_16x16x32_bf16 v[6:9], v[166:169], v[226:229], v[6:9]
	v_mfma_f32_16x16x32_bf16 v[2:5], v[170:173], v[222:225], v[2:5]
	v_mfma_f32_16x16x32_bf16 v[2:5], v[182:185], v[226:229], v[2:5]
	s_setprio 0
.Lht_skip_b:
	s_barrier
	s_add_i32 s51, s51, 2
	s_add_u32 s0, s0, 0x100
	s_addc_u32 s1, s1, 0
	s_add_u32 s49, s49, 0x100
	s_addc_u32 s50, s50, 0
	s_cmp_gt_u32 s51, 13
	s_cbranch_scc0 .LBB0_566
	s_and_b64 vcc, exec, s[18:19]
	s_cbranch_vccz .LBB0_569
	s_barrier
.LBB0_569:
	v_lshl_add_u32 v150, s46, 8, v197
	s_cmp_eq_u32 s99, 2
	s_cselect_b32 s100, 0x80, 0
	s_lshl_b32 s101, s100, 2
	v_add_u32_e32 v150, s100, v150
	s_mov_b64 s[0:1], -1
	s_cmp_gt_u32 s2, 11
	v_ashrrev_i32_e32 v151, 31, v150
	s_cbranch_scc1 .LBB0_571
	s_lshl_b32 s0, s2, 10
	s_add_i32 s0, s0, 0
	v_add_u32_e32 v134, s0, v198
	v_add_u32_e32 v134, s101, v134
	v_add_u32_e32 v135, 0x20ac0, v134
	v_add_u32_e32 v136, 0x20a80, v134
	v_add_u32_e32 v137, 0x20a40, v134
	v_add_u32_e32 v152, 0x20a00, v134
	v_add_u32_e32 v153, 0x208c0, v134
	v_add_u32_e32 v154, 0x20880, v134
	v_add_u32_e32 v155, 0x20840, v134
	v_add_u32_e32 v156, 0x20800, v134
	ds_read_b32 v134, v135
	ds_read_b32 v164, v136
	ds_read_b32 v162, v137
	ds_read_b32 v158, v152
	ds_read_b32 v160, v153
	ds_read_b32 v166, v154
	ds_read_b32 v168, v155
	ds_read_b32 v170, v156
	s_mov_b64 s[0:1], 0

.LBB0_589:
	s_waitcnt lgkmcnt(0)
	v_mad_i64_i32 v[160:161], s[2:3], v152, s76, v[170:171]
	v_mov_b32_e32 v152, v136
	v_mov_b32_e32 v153, v136
	v_pk_mul_f32 v[156:157], v[152:153], v[84:85]
	v_pk_mul_f32 v[154:155], v[136:137], v[82:83]
	v_pk_mul_f32 v[166:167], v[152:153], v[80:81]
	v_pk_mul_f32 v[168:169], v[136:137], v[78:79]
	v_cvt_pk_bf16_f32 v154, v154, v155
	v_cvt_pk_bf16_f32 v155, v156, v157
	v_cvt_pk_bf16_f32 v156, v168, v169
	v_cvt_pk_bf16_f32 v157, v166, v167
	global_store_dwordx4 v[160:161], v[154:157], off
	v_pk_mul_f32 v[166:167], v[152:153], v[72:73]
	v_pk_mul_f32 v[168:169], v[136:137], v[70:71]
	v_pk_mul_f32 v[156:157], v[152:153], v[76:77]
	v_pk_mul_f32 v[154:155], v[136:137], v[74:75]
	v_pk_mul_f32 v[68:69], v[68:69], v[158:159] op_sel_hi:[1,0]
	v_cvt_pk_bf16_f32 v154, v154, v155
	v_cvt_pk_bf16_f32 v155, v156, v157
	v_cvt_pk_bf16_f32 v156, v168, v169
	v_cvt_pk_bf16_f32 v157, v166, v167
	global_store_dwordx4 v[160:161], v[154:157], off offset:256
	s_cmp_lg_u32 s99, 0
	s_cbranch_scc1 .LBB0_615
	v_pk_mul_f32 v[66:67], v[66:67], v[158:159] op_sel_hi:[1,0]
	v_pk_mul_f32 v[64:65], v[64:65], v[158:159] op_sel_hi:[1,0]
	v_add_u32_e32 v154, 0x80, v150
	v_pk_mul_f32 v[62:63], v[62:63], v[158:159] op_sel_hi:[1,0]
	v_pk_mul_f32 v[60:61], v[60:61], v[158:159] op_sel_hi:[1,0]
	v_pk_mul_f32 v[58:59], v[58:59], v[158:159] op_sel_hi:[1,0]
	v_pk_mul_f32 v[56:57], v[56:57], v[158:159] op_sel_hi:[1,0]
	v_pk_mul_f32 v[54:55], v[54:55], v[158:159] op_sel_hi:[1,0]
	s_and_b64 vcc, exec, s[0:1]
	v_ashrrev_i32_e32 v155, 31, v154
	s_cbranch_vccnz .LBB0_593
	ds_bpermute_b32 v158, v192, v66
	ds_bpermute_b32 v159, v192, v67
	ds_bpermute_b32 v156, v192, v68
	ds_bpermute_b32 v157, v192, v69
	ds_bpermute_b32 v166, v192, v62
	ds_bpermute_b32 v167, v192, v63
	ds_bpermute_b32 v160, v192, v64
	ds_bpermute_b32 v161, v192, v65
	ds_bpermute_b32 v172, v192, v58
	ds_bpermute_b32 v173, v192, v59
	ds_bpermute_b32 v168, v192, v60
	ds_bpermute_b32 v169, v192, v61
	ds_bpermute_b32 v174, v192, v54
	ds_bpermute_b32 v175, v192, v55
	ds_bpermute_b32 v182, v192, v56
	ds_bpermute_b32 v183, v192, v57
	s_and_saveexec_b64 s[30:31], s[6:7]
	s_cbranch_execz .LBB0_592
	s_waitcnt vmcnt(2)
	v_mov_b64_e32 v[184:185], v[218:219]
	v_mov_b64_e32 v[186:187], v[220:221]
	v_mov_b64_e32 v[188:189], v[222:223]
	v_mov_b64_e32 v[190:191], v[224:225]
	v_mov_b64_e32 v[202:203], v[226:227]
	v_mov_b64_e32 v[204:205], v[228:229]
	v_mov_b64_e32 v[206:207], v[230:231]
	v_mov_b64_e32 v[208:209], v[232:233]
	global_load_dwordx4 v[218:221], v[234:235], off offset:1024
	global_load_dwordx4 v[222:225], v[234:235], off offset:1056
	global_load_dwordx4 v[226:229], v[234:235], off offset:1040
	global_load_dwordx4 v[230:233], v[234:235], off offset:1072
	v_xor_b32_e32 v135, 0x80000000, v206
	v_xor_b32_e32 v151, 0x80000000, v207
	v_xor_b32_e32 v155, 0x80000000, v208
	v_xor_b32_e32 v163, 0x80000000, v209
	v_cndmask_b32_e64 v209, v209, v163, s[4:5]
	v_cndmask_b32_e64 v208, v208, v155, s[4:5]
	v_cndmask_b32_e64 v207, v207, v151, s[4:5]
	v_cndmask_b32_e64 v206, v206, v135, s[4:5]
	s_waitcnt lgkmcnt(2)
	v_pk_mul_f32 v[174:175], v[206:207], v[174:175]
	s_waitcnt lgkmcnt(0)
	v_pk_mul_f32 v[182:183], v[208:209], v[182:183]
	v_xor_b32_e32 v135, 0x80000000, v188
	v_xor_b32_e32 v151, 0x80000000, v189
	v_xor_b32_e32 v155, 0x80000000, v190
	v_xor_b32_e32 v163, 0x80000000, v191
	v_pk_fma_f32 v[56:57], v[56:57], v[204:205], v[182:183]
	v_pk_fma_f32 v[54:55], v[54:55], v[202:203], v[174:175]
	v_cndmask_b32_e64 v175, v191, v163, s[4:5]
	v_cndmask_b32_e64 v174, v190, v155, s[4:5]
	v_cndmask_b32_e64 v183, v189, v151, s[4:5]
	v_cndmask_b32_e64 v182, v188, v135, s[4:5]
	v_pk_mul_f32 v[172:173], v[182:183], v[172:173]
	v_pk_mul_f32 v[168:169], v[174:175], v[168:169]
	v_pk_mul_f32 v[166:167], v[206:207], v[166:167]
	v_pk_mul_f32 v[160:161], v[208:209], v[160:161]
	v_pk_mul_f32 v[158:159], v[182:183], v[158:159]
	v_pk_mul_f32 v[156:157], v[174:175], v[156:157]
	v_pk_fma_f32 v[60:61], v[60:61], v[186:187], v[168:169]
	v_pk_fma_f32 v[58:59], v[58:59], v[184:185], v[172:173]
	v_pk_fma_f32 v[64:65], v[64:65], v[204:205], v[160:161]
	v_pk_fma_f32 v[62:63], v[62:63], v[202:203], v[166:167]
	v_pk_fma_f32 v[68:69], v[68:69], v[186:187], v[156:157]
	v_pk_fma_f32 v[66:67], v[66:67], v[184:185], v[158:159]
